# bundle3: bundle2 + FFT2 fused-epilogue MFMA stage with all DT loads issued up front and counted waits
# baseline (speedup 1.0000x reference)
; #define PG8_LAS __attribute__((address_space(3)))
; __device__ __forceinline__ unsigned cvt_pk_bf16(float lo, float hi) { unsigned r; asm volatile("v_cvt_pk_bf16_f32 %0, %1, %2" : "=v"(r) : "v"(lo), "v"(hi)); return r; }
;     __device__ __forceinline__ void fused(const f32x4 (&acc)[2][2][4][2], const Unit& u, int wr, int wc, int fr, int fq, PG8_LAS unsigned char* lds, int wid, int lane) const {
;         typedef __attribute__((ext_vector_type(16))) float f32x16;
;         const int k1 = u.pn >> 2;
; #pragma unroll
;         for (int m = 0; m < 4; ++m)
; #pragma unroll
;             for (int bj = 0; bj < 2; ++bj) { const f32x4 v0 = acc[0][bj][m][0], v1 = acc[0][bj][m][1];
;                 u32x4 w; w.x = cvt_pk_bf16(v0[0], v0[1]); w.y = cvt_pk_bf16(v0[2], v0[3]); w.z = cvt_pk_bf16(v1[0], v1[1]); w.w = cvt_pk_bf16(v1[2], v1[3]);
;                 *(PG8_LAS u32x4*)(lds + bj * XG + (m * 16 + fr) * XP + (wr * 128 + wc * 32 + 8 * fq) * 2) = w; }
;         asm volatile("s_waitcnt lgkmcnt(0)\n\ts_barrier" ::: "memory");
;         const int g2 = wid >> 2, cq = wid & 3, r32 = lane & 31, hi = lane >> 5;
;         const bf16_t* dtp = DT + (32 * cq + r32) * 256 + 8 * hi;
;         const PG8_LAS unsigned char* xp = lds + g2 * XG + r32 * XP + 16 * hi;
;         f32x16 y0 = {}, y1 = {};
; #pragma unroll
;         for (int kh = 0; kh < 2; ++kh) { bf16x8 a[8];
; #pragma unroll
;             for (int ks = 0; ks < 8; ++ks) a[ks] = *(const bf16x8*)(dtp + 16 * (8 * kh + ks));
; #pragma unroll
;             for (int ks = 0; ks < 8; ++ks) { const bf16x8 b0 = *(const PG8_LAS bf16x8*)(xp + 32 * (8 * kh + ks)), b1 = *(const PG8_LAS bf16x8*)(xp + 32 * XP + 32 * (8 * kh + ks));
;                 y0 = __builtin_amdgcn_mfma_f32_32x32x16_bf16(a[ks], b0, y0, 0, 0, 0); y1 = __builtin_amdgcn_mfma_f32_32x32x16_bf16(a[ks], b1, y1, 0, 0, 0); } }
.LBB0_549:
	s_and_b32 s11, s11, 0xffffff00
	s_lshl_b32 s13, s13, 6
	s_add_i32 s11, s11, 0
	s_add_i32 s11, s11, s13
	v_mul_u32_u24_e32 v65, 0x210, v65
	v_add3_u32 v65, s11, v66, v65
	s_lshl_b32 s10, s10, 5
	s_waitcnt vmcnt(0)
	s_barrier
	v_cvt_pk_bf16_f32 v56, v56, v57
	v_cvt_pk_bf16_f32 v57, v58, v59
	v_cvt_pk_bf16_f32 v58, v48, v49
	v_cvt_pk_bf16_f32 v59, v50, v51
	ds_write_b128 v65, v[56:59]
	v_cvt_pk_bf16_f32 v48, v60, v61
	v_cvt_pk_bf16_f32 v49, v62, v63
	v_cvt_pk_bf16_f32 v50, v52, v53
	v_cvt_pk_bf16_f32 v51, v54, v55
	ds_write_b128 v65, v[48:51] offset:33792
	v_cvt_pk_bf16_f32 v40, v40, v41
	v_cvt_pk_bf16_f32 v41, v42, v43
	v_cvt_pk_bf16_f32 v42, v32, v33
	v_cvt_pk_bf16_f32 v43, v34, v35
	ds_write_b128 v65, v[40:43] offset:8448
	v_cvt_pk_bf16_f32 v32, v44, v45
	v_cvt_pk_bf16_f32 v33, v46, v47
	v_cvt_pk_bf16_f32 v34, v36, v37
	v_cvt_pk_bf16_f32 v35, v38, v39
	ds_write_b128 v65, v[32:35] offset:42240
	v_cvt_pk_bf16_f32 v24, v24, v25
	v_cvt_pk_bf16_f32 v25, v26, v27
	v_cvt_pk_bf16_f32 v26, v16, v17
	v_cvt_pk_bf16_f32 v27, v18, v19
	ds_write_b128 v65, v[24:27] offset:16896
	v_cvt_pk_bf16_f32 v16, v28, v29
	v_cvt_pk_bf16_f32 v17, v30, v31
	v_cvt_pk_bf16_f32 v18, v20, v21
	v_cvt_pk_bf16_f32 v19, v22, v23
	ds_write_b128 v65, v[16:19] offset:50688
	v_cvt_pk_bf16_f32 v8, v8, v9
	v_cvt_pk_bf16_f32 v9, v10, v11
	v_cvt_pk_bf16_f32 v10, v0, v1
	v_cvt_pk_bf16_f32 v11, v2, v3
	ds_write_b128 v65, v[8:11] offset:25344
	v_cvt_pk_bf16_f32 v0, v12, v13
	v_cvt_pk_bf16_f32 v1, v14, v15
	v_cvt_pk_bf16_f32 v2, v4, v5
	v_cvt_pk_bf16_f32 v3, v6, v7
	ds_write_b128 v65, v[0:3] offset:59136
	v_and_b32_e32 v65, 31, v64
	s_and_b32 s10, s10, 0x60
	v_or_b32_e32 v0, s10, v65
	v_bfe_u32 v58, v64, 5, 1
	v_lshlrev_b32_e32 v176, 9, v0
	v_lshl_add_u64 v[0:1], s[8:9], 0, v[176:177]
	v_lshlrev_b32_e32 v4, 4, v58
	v_mov_b32_e32 v5, v177
	v_lshl_add_u64 v[8:9], v[0:1], 0, v[4:5]
	s_mov_b32 s11, 0x500000
	v_add_co_u32_e32 v0, vcc, s11, v8
	s_waitcnt lgkmcnt(0)
	s_barrier
	s_mov_b64 s[14:15], 0x500000
	s_nop 0
	v_addc_co_u32_e32 v1, vcc, 0, v9, vcc
	v_lshl_add_u64 v[56:57], v[8:9], 0, s[14:15]
	global_load_dwordx4 v[68:71], v[56:57], off
	global_load_dwordx4 v[72:75], v[56:57], off offset:32
	global_load_dwordx4 v[76:79], v[56:57], off offset:64
	global_load_dwordx4 v[80:83], v[56:57], off offset:96
	global_load_dwordx4 v[84:87], v[56:57], off offset:128
	global_load_dwordx4 v[88:91], v[56:57], off offset:160
	global_load_dwordx4 v[92:95], v[56:57], off offset:192
	global_load_dwordx4 v[96:99], v[56:57], off offset:224
	global_load_dwordx4 v[100:103], v[56:57], off offset:256
	global_load_dwordx4 v[104:107], v[56:57], off offset:288
	global_load_dwordx4 v[108:111], v[56:57], off offset:320
	global_load_dwordx4 v[112:115], v[56:57], off offset:352
	global_load_dwordx4 v[116:119], v[56:57], off offset:384
	global_load_dwordx4 v[120:123], v[56:57], off offset:416
	global_load_dwordx4 v[128:131], v[56:57], off offset:448
	global_load_dwordx4 v[132:135], v[56:57], off offset:480
	s_mul_i32 s11, s5, 0x8400
	s_add_i32 s11, s11, 0
	v_mul_u32_u24_e32 v5, 0x210, v65
	v_add3_u32 v60, s11, v5, v4
	v_lshlrev_b32_e32 v176, 3, v58
	s_ashr_i32 s11, s12, 2
	v_lshl_add_u32 v64, v65, 7, s11
	v_ashrrev_i32_e32 v65, 31, v64
	v_lshlrev_b64 v[64:65], 12, v[64:65]
	v_lshl_add_u64 v[64:65], s[8:9], 0, v[64:65]
	s_lshl_b32 s8, s12, 1
	s_and_b32 s8, s8, 6
	s_add_i32 s8, s8, s5
	s_lshl_b32 s8, s8, 7
	s_ashr_i32 s9, s8, 31
	s_mov_b32 s5, 0xc800000
	ds_read_b128 v[136:139], v60
	ds_read_b128 v[140:143], v60 offset:16896
	ds_read_b128 v[144:147], v60 offset:32
	ds_read_b128 v[148:151], v60 offset:16928
	ds_read_b128 v[152:155], v60 offset:64
	ds_read_b128 v[156:159], v60 offset:16960
	s_waitcnt vmcnt(15) lgkmcnt(4)
	v_mfma_f32_32x32x16_bf16 v[16:31], v[68:71], v[136:139], 0
	v_mfma_f32_32x32x16_bf16 v[0:15], v[68:71], v[140:143], 0
	ds_read_b128 v[136:139], v60 offset:96
	ds_read_b128 v[140:143], v60 offset:16992
	s_waitcnt vmcnt(14) lgkmcnt(4)
	v_mfma_f32_32x32x16_bf16 v[16:31], v[72:75], v[144:147], v[16:31]
	v_mfma_f32_32x32x16_bf16 v[0:15], v[72:75], v[148:151], v[0:15]
	ds_read_b128 v[144:147], v60 offset:128
	ds_read_b128 v[148:151], v60 offset:17024
	s_waitcnt vmcnt(13) lgkmcnt(4)
	v_mfma_f32_32x32x16_bf16 v[16:31], v[76:79], v[152:155], v[16:31]
	v_mfma_f32_32x32x16_bf16 v[0:15], v[76:79], v[156:159], v[0:15]
	ds_read_b128 v[152:155], v60 offset:160
	ds_read_b128 v[156:159], v60 offset:17056
	s_waitcnt vmcnt(12) lgkmcnt(4)
	v_mfma_f32_32x32x16_bf16 v[16:31], v[80:83], v[136:139], v[16:31]
	v_mfma_f32_32x32x16_bf16 v[0:15], v[80:83], v[140:143], v[0:15]
	ds_read_b128 v[136:139], v60 offset:192
	ds_read_b128 v[140:143], v60 offset:17088
	s_waitcnt vmcnt(11) lgkmcnt(4)
	v_mfma_f32_32x32x16_bf16 v[16:31], v[84:87], v[144:147], v[16:31]
	v_mfma_f32_32x32x16_bf16 v[0:15], v[84:87], v[148:151], v[0:15]
	ds_read_b128 v[144:147], v60 offset:224
	ds_read_b128 v[148:151], v60 offset:17120
	s_waitcnt vmcnt(10) lgkmcnt(4)
	v_mfma_f32_32x32x16_bf16 v[16:31], v[88:91], v[152:155], v[16:31]
	v_mfma_f32_32x32x16_bf16 v[0:15], v[88:91], v[156:159], v[0:15]
	ds_read_b128 v[152:155], v60 offset:256
	ds_read_b128 v[156:159], v60 offset:17152
	s_waitcnt vmcnt(9) lgkmcnt(4)
	v_mfma_f32_32x32x16_bf16 v[16:31], v[92:95], v[136:139], v[16:31]
	v_mfma_f32_32x32x16_bf16 v[0:15], v[92:95], v[140:143], v[0:15]
	ds_read_b128 v[136:139], v60 offset:288
	ds_read_b128 v[140:143], v60 offset:17184
	s_waitcnt vmcnt(8) lgkmcnt(4)
; #define PG8_LAS __attribute__((address_space(3)))
;     __device__ __forceinline__ void fused(const f32x4 (&acc)[2][2][4][2], const Unit& u, int wr, int wc, int fr, int fq, PG8_LAS unsigned char* lds, int wid, int lane) const {
;     ...
;         for (int kh = 0; kh < 2; ++kh) { bf16x8 a[8];
; #pragma unroll
;             for (int ks = 0; ks < 8; ++ks) a[ks] = *(const bf16x8*)(dtp + 16 * (8 * kh + ks));
; #pragma unroll
;             for (int ks = 0; ks < 8; ++ks) { const bf16x8 b0 = *(const PG8_LAS bf16x8*)(xp + 32 * (8 * kh + ks)), b1 = *(const PG8_LAS bf16x8*)(xp + 32 * XP + 32 * (8 * kh + ks));
;                 y0 = __builtin_amdgcn_mfma_f32_32x32x16_bf16(a[ks], b0, y0, 0, 0, 0); y1 = __builtin_amdgcn_mfma_f32_32x32x16_bf16(a[ks], b1, y1, 0, 0, 0); } }
;         bf16_t* yb = YA + (size_t)(k1 + 128 * r32) * 2048 + (2 * (u.pn & 3) + g2) * 128 + 32 * cq + 4 * hi;
; #pragma unroll
;         for (int q = 0; q < 4; ++q) {
;             u32x2 w0; w0.x = pk_rne(y0[4 * q], y0[4 * q + 1]); w0.y = pk_rne(y0[4 * q + 2], y0[4 * q + 3]); *(u32x2*)(yb + 8 * q) = w0;
;             u32x2 w1; w1.x = pk_rne(y1[4 * q], y1[4 * q + 1]); w1.y = pk_rne(y1[4 * q + 2], y1[4 * q + 3]); *(u32x2*)(yb + (size_t)(128 * 32) * 2048 + 8 * q) = w1; }
;         asm volatile("s_waitcnt lgkmcnt(0)\n\ts_barrier" ::: "memory");
	v_mfma_f32_32x32x16_bf16 v[16:31], v[96:99], v[144:147], v[16:31]
	v_mfma_f32_32x32x16_bf16 v[0:15], v[96:99], v[148:151], v[0:15]
	ds_read_b128 v[144:147], v60 offset:320
	ds_read_b128 v[148:151], v60 offset:17216
	s_waitcnt vmcnt(7) lgkmcnt(4)
	v_mfma_f32_32x32x16_bf16 v[16:31], v[100:103], v[152:155], v[16:31]
	v_mfma_f32_32x32x16_bf16 v[0:15], v[100:103], v[156:159], v[0:15]
	ds_read_b128 v[152:155], v60 offset:352
	ds_read_b128 v[156:159], v60 offset:17248
	s_waitcnt vmcnt(6) lgkmcnt(4)
	v_mfma_f32_32x32x16_bf16 v[16:31], v[104:107], v[136:139], v[16:31]
	v_mfma_f32_32x32x16_bf16 v[0:15], v[104:107], v[140:143], v[0:15]
	ds_read_b128 v[136:139], v60 offset:384
	ds_read_b128 v[140:143], v60 offset:17280
	s_waitcnt vmcnt(5) lgkmcnt(4)
	v_mfma_f32_32x32x16_bf16 v[16:31], v[108:111], v[144:147], v[16:31]
	v_mfma_f32_32x32x16_bf16 v[0:15], v[108:111], v[148:151], v[0:15]
	ds_read_b128 v[144:147], v60 offset:416
	ds_read_b128 v[148:151], v60 offset:17312
	s_waitcnt vmcnt(4) lgkmcnt(4)
	v_mfma_f32_32x32x16_bf16 v[16:31], v[112:115], v[152:155], v[16:31]
	v_mfma_f32_32x32x16_bf16 v[0:15], v[112:115], v[156:159], v[0:15]
	ds_read_b128 v[152:155], v60 offset:448
	ds_read_b128 v[156:159], v60 offset:17344
	s_waitcnt vmcnt(3) lgkmcnt(4)
	v_mfma_f32_32x32x16_bf16 v[16:31], v[116:119], v[136:139], v[16:31]
	v_mfma_f32_32x32x16_bf16 v[0:15], v[116:119], v[140:143], v[0:15]
	ds_read_b128 v[136:139], v60 offset:480
	ds_read_b128 v[140:143], v60 offset:17376
	s_waitcnt vmcnt(2) lgkmcnt(4)
	v_mfma_f32_32x32x16_bf16 v[16:31], v[120:123], v[144:147], v[16:31]
	v_mfma_f32_32x32x16_bf16 v[0:15], v[120:123], v[148:151], v[0:15]
	s_waitcnt vmcnt(1) lgkmcnt(2)
	v_mfma_f32_32x32x16_bf16 v[16:31], v[128:131], v[152:155], v[16:31]
	v_mfma_f32_32x32x16_bf16 v[0:15], v[128:131], v[156:159], v[0:15]
	s_waitcnt vmcnt(0) lgkmcnt(0)
	v_mfma_f32_32x32x16_bf16 v[16:31], v[132:135], v[136:139], v[16:31]
	v_mfma_f32_32x32x16_bf16 v[0:15], v[132:135], v[140:143], v[0:15]
	v_lshl_add_u64 v[48:49], s[8:9], 1, v[64:65]
	s_lshl_b32 s8, s10, 1
	s_mov_b32 s9, s24
	v_lshl_add_u64 v[48:49], v[48:49], 0, s[8:9]
	v_lshl_add_u64 v[48:49], v[48:49], 0, v[176:177]
	s_mov_b64 s[8:9], 0xc800000
	v_lshl_add_u64 v[50:51], v[48:49], 0, s[8:9]
	s_nop 15
	v_bfe_u32 v56, v16, 16, 1
	v_add3_u32 v16, v16, v56, s65
	v_bfe_u32 v32, v17, 16, 1
	v_lshrrev_b32_e32 v16, 16, v16
	v_add3_u32 v17, v17, v32, s65
	v_and_or_b32 v16, v17, s53, v16
	v_bfe_u32 v17, v18, 16, 1
	v_add3_u32 v17, v18, v17, s65
	v_bfe_u32 v18, v19, 16, 1
	v_lshrrev_b32_e32 v17, 16, v17
	v_add3_u32 v18, v19, v18, s65
	v_and_or_b32 v17, v18, s53, v17
	v_add_co_u32_e32 v18, vcc, s5, v48
	s_mov_b32 s5, 0xd800000
	s_nop 0
	v_addc_co_u32_e32 v19, vcc, 0, v49, vcc
	global_store_dwordx2 v[18:19], v[16:17], off
	s_nop 1
	v_bfe_u32 v16, v0, 16, 1
	v_add3_u32 v0, v0, v16, s65
	v_bfe_u32 v16, v1, 16, 1
	v_lshrrev_b32_e32 v0, 16, v0
	v_add3_u32 v1, v1, v16, s65
	v_and_or_b32 v0, v1, s53, v0
	v_bfe_u32 v1, v2, 16, 1
	v_add3_u32 v1, v2, v1, s65
	v_bfe_u32 v2, v3, 16, 1
	v_lshrrev_b32_e32 v1, 16, v1
	v_add3_u32 v2, v3, v2, s65
	v_and_or_b32 v1, v2, s53, v1
	v_add_co_u32_e32 v2, vcc, s5, v48
	v_bfe_u32 v16, v23, 16, 1
	s_nop 0
	v_addc_co_u32_e32 v3, vcc, 0, v49, vcc
	global_store_dwordx2 v[2:3], v[0:1], off
	v_bfe_u32 v0, v20, 16, 1
	v_add3_u32 v0, v20, v0, s65
	v_bfe_u32 v1, v21, 16, 1
	v_lshrrev_b32_e32 v0, 16, v0
	v_add3_u32 v1, v21, v1, s65
	v_and_or_b32 v0, v1, s53, v0
	v_bfe_u32 v1, v22, 16, 1
	v_add3_u32 v1, v22, v1, s65
	v_lshrrev_b32_e32 v1, 16, v1
	v_add3_u32 v16, v23, v16, s65
	v_and_or_b32 v1, v16, s53, v1
	global_store_dwordx2 v[50:51], v[0:1], off offset:16
	v_bfe_u32 v0, v4, 16, 1
	v_add3_u32 v0, v4, v0, s65
	v_bfe_u32 v1, v5, 16, 1
	v_lshrrev_b32_e32 v0, 16, v0
	v_add3_u32 v1, v5, v1, s65
	v_and_or_b32 v0, v1, s53, v0
	v_bfe_u32 v1, v6, 16, 1
	v_add3_u32 v1, v6, v1, s65
	v_bfe_u32 v4, v7, 16, 1
	v_lshrrev_b32_e32 v1, 16, v1
	v_add3_u32 v4, v7, v4, s65
	v_and_or_b32 v1, v4, s53, v1
	global_store_dwordx2 v[2:3], v[0:1], off offset:16
	v_bfe_u32 v0, v24, 16, 1
	v_add3_u32 v0, v24, v0, s65
	v_bfe_u32 v1, v25, 16, 1
	v_lshrrev_b32_e32 v0, 16, v0
	v_add3_u32 v1, v25, v1, s65
	v_and_or_b32 v0, v1, s53, v0
	v_bfe_u32 v1, v26, 16, 1
	v_add3_u32 v1, v26, v1, s65
	v_bfe_u32 v4, v27, 16, 1
	v_lshrrev_b32_e32 v1, 16, v1
	v_add3_u32 v4, v27, v4, s65
	v_and_or_b32 v1, v4, s53, v1
	global_store_dwordx2 v[50:51], v[0:1], off offset:32
	v_bfe_u32 v0, v8, 16, 1
	v_add3_u32 v0, v8, v0, s65
	v_bfe_u32 v1, v9, 16, 1
	v_lshrrev_b32_e32 v0, 16, v0
	v_add3_u32 v1, v9, v1, s65
	v_and_or_b32 v0, v1, s53, v0
	v_bfe_u32 v1, v10, 16, 1
	v_add3_u32 v1, v10, v1, s65
	v_bfe_u32 v4, v11, 16, 1
	v_lshrrev_b32_e32 v1, 16, v1
	v_add3_u32 v4, v11, v4, s65
	v_and_or_b32 v1, v4, s53, v1
	global_store_dwordx2 v[2:3], v[0:1], off offset:32
	v_bfe_u32 v0, v28, 16, 1
	v_add3_u32 v0, v28, v0, s65
	v_bfe_u32 v1, v29, 16, 1
	v_lshrrev_b32_e32 v0, 16, v0
	v_add3_u32 v1, v29, v1, s65
	v_and_or_b32 v0, v1, s53, v0
	v_bfe_u32 v1, v30, 16, 1
	v_add3_u32 v1, v30, v1, s65
	v_bfe_u32 v4, v31, 16, 1
	v_lshrrev_b32_e32 v1, 16, v1
	v_add3_u32 v4, v31, v4, s65
	v_and_or_b32 v1, v4, s53, v1
	global_store_dwordx2 v[50:51], v[0:1], off offset:48
	v_bfe_u32 v0, v12, 16, 1
	v_add3_u32 v0, v12, v0, s65
	v_bfe_u32 v1, v13, 16, 1
	v_lshrrev_b32_e32 v0, 16, v0
	v_add3_u32 v1, v13, v1, s65
	v_and_or_b32 v0, v1, s53, v0
	v_bfe_u32 v1, v14, 16, 1
	v_add3_u32 v1, v14, v1, s65
	v_bfe_u32 v4, v15, 16, 1
	v_lshrrev_b32_e32 v1, 16, v1
	v_add3_u32 v4, v15, v4, s65
	v_and_or_b32 v1, v4, s53, v1
	global_store_dwordx2 v[2:3], v[0:1], off offset:48
	s_waitcnt lgkmcnt(0)
	s_barrier
